# attention queue hybrid order: stream pairs for L2 locality, last four streams merged for tail balance
# speedup vs baseline: 1.0096x; 1.0096x over previous
; template <int MODE>
; __device__ __forceinline__ void attn_unit(LAS unsigned char* lds, const Ptrs& P, int nq, int nt_block, int qpos0, bool sample, int h,
;                                           const float* relb  , const float* lamp, const float* subg, bf16_t* Obase  , int wv) {
;     ...
;     constexpr int NQF = (MODE == 0) ? 4 : 6;
;     bf16x8 qf[NQF];
;     {
;         const int qr = wact ? (wid * 32 + r32) : 0;
;         const bf16_t* qp = P.Q + (size_t)qr * P.ldq + hi * 8;
; #pragma unroll
;         for (int i = 0; i < NQF; ++i) qf[i] = *(const bf16x8*)(qp + i * 16);
;     }
;     LAS float* bt = (LAS float*)(lds + BT_OFF);
;     float cbias = 0.f;
;     if (MODE == 0) {
;         if (tid < 256) {
;             const int rel = tid - 192;
;             const int n = rel < 0 ? -rel : rel;
;             int bk = rel > 0 ? 16 : 0;
;             if (n < 8) bk += n; else { int lg = 2 + (31 - __clz(n * n)); bk += (lg > 15 ? 15 : lg); }
;             bt[tid] = relb[bk * 6 + h] * LOG2E;
;         }
;         cbias = relb[15 * 6 + h] * LOG2E;
;     }
;     const bf16_t* kg = P.K + (size_t)lane * P.ldk + wid * 8;
;     const bf16_t* krg = (MODE == 1) ? (P.Kr + (size_t)lane * 32 + (wid & 3) * 8) : nullptr;
; __device__ __forceinline__ void attention_phase(const Args& a, int ci, int l, LAS unsigned char* lds, int wv) {
;     ...
;         } else if (qi < QS + QP) {
;             const int i2 = qi - QS; const int pr = i2 >> 5, within = i2 & 31; const int qb = 15 - (within >> 1);
;             const int stream = x * 24 + pr * 2 + (within & 1);
;             const int type = stream / 96, bh = stream % 96, b = bh / 6, h = bh % 6;
;             const int qrow0 = b * 4096 + qb * 256; const size_t kv0 = (size_t)b * 4096;
;             if (type == 0) {
;                 att::Ptrs P{U + (size_t)qrow0 * INC + h * 64, INC, U + kv0 * INC + 384 + h * 64, INC, nullptr, U + kv0 * INC + 768 + h * 64, INC};
;                 att::attn_unit<0>(lds, P, 256, 4 * (qb + 1), qb * 256, false, h, a.in[19], lamp, a.in[18] + l * 64, MIX + (size_t)qrow0 * 1024 + h * 64, wv);
;             } else {
;                 att::Ptrs P{QC + (size_t)qrow0 * 576 + h * 96, 576, KVX + kv0 * 768 + h * 128, 768, KR + kv0 * 32, KVX + kv0 * 768 + h * 128 + 64, 768};
;                 att::attn_unit<1>(lds, P, 256, 4 * (qb + 1), qb * 256, false, h, nullptr, lamp, nullptr, MIX + (size_t)qrow0 * 1024 + 640 + h * 64, wv);
.LBB0_1178:
	s_and_b64 vcc, exec, s[2:3]
	s_cbranch_vccz .LBB0_1254
	s_add_i32 s2, s14, -12
	s_bfe_u32 s8, s2, 0x40001
	s_lshr_b32 s4, s2, 5
	s_cmpk_lt_u32 s2, 0x140
	s_cbranch_scc1 .Lattq_a
	s_addk_i32 s2, 0xfec0
	s_lshr_b32 s8, s2, 2
	s_bfe_u32 s4, s2, 0x10001
	s_add_i32 s4, s4, 10
.Lattq_a:
	s_mul_i32 s3, s5, 12
	s_add_i32 s4, s4, s3
	s_and_b32 s2, s14, 1
	s_mul_i32 s2, s2, 0x60
	s_add_i32 s3, s4, s2
	s_add_i32 s4, s3, 0xffffffa0
	s_cmpk_lt_u32 s2, 0x60
	s_cselect_b32 s3, s3, s4
	s_mul_hi_u32 s4, s3, 0xaaaaaaab
	s_lshr_b32 s4, s4, 2
	s_mul_i32 s15, s4, 6
	s_sub_i32 s22, s3, s15
	s_lshl_b32 s3, s8, 8
	s_lshl_b32 s24, s4, 12
	s_xor_b32 s15, s3, 0xf00
	s_or_b32 s20, s24, s15
	s_cmpk_gt_u32 s2, 0x5f
	s_mov_b32 s21, s83
	s_mov_b64 s[2:3], -1
	s_cbranch_scc0 .LBB0_1214
	s_mul_i32 s3, s20, 0x480
	v_readlane_b32 s4, v252, 52
	s_mul_hi_u32 s2, s20, 0x480
	s_add_u32 s4, s4, s3
	v_readlane_b32 s3, v252, 53
	s_mul_i32 s82, s22, 0x60
	s_addc_u32 s23, s3, s2
	s_lshl_b64 s[2:3], s[82:83], 1
	s_add_u32 s26, s4, s2
	s_addc_u32 s27, s23, s3
	s_mul_i32 s3, s24, 0x600
	v_readlane_b32 s4, v252, 54
	s_mul_hi_u32 s2, s24, 0x600
	s_add_u32 s3, s4, s3
	v_readlane_b32 s4, v252, 55
	s_addc_u32 s2, s4, s2
	s_lshl_b32 s4, s22, 8
	s_mov_b32 s25, s83
	s_add_u32 s28, s3, s4
	s_addc_u32 s29, s2, 0
	s_lshl_b64 s[2:3], s[24:25], 6
	v_mov_b32_e32 v8, v215
	s_add_u32 s30, s34, s2
	s_addc_u32 s31, s35, s3
	v_readfirstlane_b32 s4, v8
	s_ashr_i32 s2, s4, 6
	v_and_b32_e32 v6, 31, v8
	s_lshl_b32 s3, s2, 5
	s_cmp_lt_i32 s2, 8
	v_or_b32_e32 v164, s3, v6
	s_movk_i32 s23, 0x240
	v_mad_i64_i32 v[0:1], s[34:35], v164, s23, 0
	s_cselect_b64 s[38:39], -1, 0
	v_bfe_u32 v7, v8, 5, 1
	v_cndmask_b32_e64 v1, 0, v1, s[38:39]
	v_cndmask_b32_e64 v0, 0, v0, s[38:39]
	v_lshl_add_u64 v[0:1], v[0:1], 1, s[26:27]
	v_lshlrev_b32_e32 v4, 4, v7
	v_lshl_add_u64 v[10:11], v[0:1], 0, v[4:5]
	v_and_b32_e32 v9, 63, v8
	global_load_dwordx4 v[0:3], v[10:11], off
	global_load_dwordx4 v[100:103], v[10:11], off offset:32
	global_load_dwordx4 v[104:107], v[10:11], off offset:64
	global_load_dwordx4 v[108:111], v[10:11], off offset:96
	global_load_dwordx4 v[112:115], v[10:11], off offset:128
	global_load_dwordx4 v[116:119], v[10:11], off offset:160
	v_mov_b64_e32 v[10:11], s[28:29]
	v_mad_u64_u32 v[10:11], s[26:27], v9, s62, v[10:11]
	s_lshl_b32 s26, s2, 3
	s_ashr_i32 s27, s26, 31
	v_lshlrev_b32_e32 v4, 6, v9
	s_and_b32 s23, s2, 3
	v_lshl_add_u64 v[166:167], s[26:27], 1, v[10:11]
	v_lshl_add_u64 v[10:11], s[30:31], 0, v[4:5]
	s_lshl_b32 s82, s23, 4
	v_bfe_u32 v4, v8, 2, 4
	v_or_b32_e32 v4, s82, v4
	v_mul_u32_u24_e32 v4, 0x300, v4
	v_lshlrev_b32_e32 v4, 1, v4
	s_ashr_i32 s4, s4, 3
	v_lshl_add_u64 v[12:13], s[28:29], 0, v[4:5]
	s_and_b32 s26, s4, 0xffffffe0
	v_lshlrev_b32_e32 v4, 3, v8
	s_ashr_i32 s27, s26, 31
	v_and_b32_e32 v172, 24, v4
	v_lshl_add_u64 v[12:13], s[26:27], 1, v[12:13]
	v_lshlrev_b32_e32 v4, 1, v172
	v_lshl_add_u64 v[168:169], v[12:13], 0, v[4:5]
	global_load_dwordx4 v[120:123], v[166:167], off
	global_load_dwordx4 v[124:127], v[168:169], off offset:128
	s_cmp_lt_i32 s2, 4
	s_cselect_b64 s[26:27], -1, 0
	s_cmp_gt_i32 s2, 3
	s_cselect_b64 s[28:29], -1, 0
	v_lshl_add_u64 v[170:171], v[10:11], 0, s[82:83]
	s_and_b64 vcc, exec, s[28:29]
	s_cbranch_vccnz .LBB0_1183
	global_load_dwordx4 v[128:131], v[170:171], off
	s_branch .LBB0_1184
